# XCD-affine rowpass row mapping: each XCD normalises the rows its own GEMM tiles just wrote (freshest half first), on top of trim+defer
# speedup vs baseline: 1.0024x; 1.0017x over previous
; #define tid fresh_tid(wave_s)
; __device__ __forceinline__ void rowpass(const bf16_t* y, const float* hin, float* hout, const float* g1, const float* g2, bf16_t* a, int tid, int bx) {
;     const int lane = tid & 63, wave = tid >> 6;
;     for (int row0 = (bx * 8 + wave) * 2; row0 < MTOK; row0 += gridDim.x * 16) {
.LBB0_227:
	v_mov_b32_e32 v0, v173
	s_mov_b32 s0, 0x8000
	v_ashrrev_i32_e32 v1, 5, v0
	v_and_b32_e32 v1, -2, v1
	v_lshl_add_u32 v44, s69, 4, v1
	s_mov_b32 s100, 0
	s_cmpk_lg_u32 s3, 0x100
	s_cbranch_scc1 .Lrp_map_done
	s_and_b32 s101, s69, 7
	s_lshl_b32 s101, s101, 12
	s_lshr_b32 s100, s69, 3
	s_lshl_b32 s100, s100, 4
	s_add_i32 s100, s100, 0x800
	v_add_u32_e32 v242, s100, v1
	v_add_u32_e32 v44, s101, v242
	s_mov_b32 s100, 8
.Lrp_map_done:
	v_cmp_gt_i32_e32 vcc, s0, v44
	s_and_saveexec_b64 s[20:21], vcc
	s_cbranch_execz .LBB0_232
	v_lshlrev_b32_e32 v0, 2, v0
	v_and_b32_e32 v0, 0xfc, v0
	v_lshlrev_b32_e32 v154, 1, v0
	v_lshl_add_u64 v[46:47], s[26:27], 0, v[154:155]
	v_lshlrev_b32_e32 v154, 2, v0
	v_and_b32_e32 v0, 64, v172
	v_readlane_b32 s25, v244, 36
	v_add_u32_e32 v0, 64, v0
	v_xor_b32_e32 v1, 32, v172
	s_cmp_eq_u32 s25, 4
	v_cmp_lt_i32_e32 vcc, v1, v0
	s_cselect_b32 s0, 0, 0x78
	v_readlane_b32 s14, v244, 34
	v_cndmask_b32_e32 v1, v172, v1, vcc
	v_readlane_b32 s15, v244, 35
	s_add_u32 s0, s14, s0
	s_mov_b32 s23, s7
	v_lshlrev_b32_e32 v96, 2, v1
	v_xor_b32_e32 v1, 16, v172
	s_addc_u32 s1, s15, 0
	s_lshl_b64 s[18:19], s[22:23], 14
	v_readlane_b32 s28, v244, 39
	v_cmp_lt_i32_e32 vcc, v1, v0
	v_readlane_b32 s29, v244, 40
	s_add_u32 s6, s28, s18
	v_cndmask_b32_e32 v1, v172, v1, vcc
	s_addc_u32 s17, s29, s19
	v_lshlrev_b32_e32 v97, 2, v1
	v_xor_b32_e32 v1, 8, v172
	s_add_u32 s18, s6, 0x2000
	v_cmp_lt_i32_e32 vcc, v1, v0
	s_addc_u32 s19, s17, 0
	s_add_u32 s23, s6, 0x4000
	v_cndmask_b32_e32 v1, v172, v1, vcc
	v_lshlrev_b32_e32 v98, 2, v1
	v_xor_b32_e32 v1, 4, v172
	s_addc_u32 s24, s17, 0
	v_cmp_lt_i32_e32 vcc, v1, v0
	s_cmp_lt_u32 s25, 24
	s_cselect_b32 s23, s23, 0
	v_cndmask_b32_e32 v1, v172, v1, vcc
	s_cselect_b32 s24, s24, 0
	s_cmp_eq_u32 s16, 4
	v_lshlrev_b32_e32 v99, 2, v1
	v_xor_b32_e32 v1, 2, v172
	s_load_dwordx2 s[0:1], s[0:1], 0x0
	s_nop 0
	s_load_dwordx2 s[14:15], s[14:15], 0x78
	s_cselect_b32 s28, s18, s23
	s_movk_i32 s18, 0x3000
	v_cmp_lt_i32_e32 vcc, v1, v0
	s_cselect_b32 s18, 0x1000, s18
	s_cselect_b32 s29, s19, s24
	v_cndmask_b32_e32 v1, v172, v1, vcc
	s_add_u32 s18, s6, s18
	s_waitcnt vmcnt(0)
	v_lshlrev_b32_e32 v100, 2, v1
	v_xor_b32_e32 v1, 1, v172
	s_addc_u32 s19, s17, 0
	v_cmp_lt_i32_e32 vcc, v1, v0
	s_cmp_lg_u64 s[28:29], 0
	s_waitcnt lgkmcnt(0)
	v_lshl_add_u64 v[48:49], s[0:1], 0, v[154:155]
	v_cndmask_b32_e32 v0, v172, v1, vcc
	v_lshl_add_u64 v[50:51], s[18:19], 0, v[154:155]
	v_lshl_add_u64 v[52:53], s[14:15], 0, v[154:155]
	s_mov_b64 s[18:19], 0
	s_cselect_b64 s[24:25], -1, 0
	v_lshl_add_u64 v[54:55], s[28:29], 0, v[154:155]
	v_lshlrev_b32_e32 v101, 2, v0
	s_branch .LBB0_230
.LBB0_229:
	s_cmp_eq_u32 s100, 0
	s_cbranch_scc1 .Lrp_ctl_orig
	v_add_u32_e32 v242, 0x200, v242
	v_and_b32_e32 v242, 0xfff, v242
	v_add_u32_e32 v44, s101, v242
	s_add_i32 s100, s100, -1
	s_cmp_eq_u32 s100, 0
	s_cbranch_scc1 .LBB0_232
	s_branch .LBB0_230
